# v36 + attention unit order interleaved: (big,s0),(small,s0),(big,s1),(small,s1) for tighter K/V L2 sharing
# baseline (speedup 1.0000x reference)
.LBB0_300:
	s_lshr_b32 s13, s9, 1
	s_bitcmp0_b32 s9, 0
	s_cselect_b32 s48, s92, s91
	s_lshl_b32 s0, s13, 7
	s_add_u32 s4, s93, s0
	s_addc_u32 s10, s94, 0
	s_waitcnt lgkmcnt(1)
	v_mov_b32_e32 v36, v0
	s_add_u32 s0, s95, s0
	s_addc_u32 s1, s96, 0
	v_readfirstlane_b32 s5, v36
	s_ashr_i32 s12, s5, 6
	s_lshl_b32 s49, s48, 8
	s_lshl_b32 s44, s12, 5
	s_add_i32 s40, s44, s49
	s_ashr_i32 s41, s40, 31
	v_and_b32_e32 v232, 63, v36
	s_lshl_b64 s[30:31], s[40:41], 12
	s_add_u32 s42, s4, s30
	v_lshlrev_b32_e32 v2, 12, v232
	s_addc_u32 s43, s10, s31
	s_waitcnt vmcnt(3)
	v_lshl_add_u64 v[4:5], s[0:1], 0, v[2:3]
	s_lshl_b32 s0, s12, 3
	s_ashr_i32 s1, s0, 31
	v_lshl_add_u64 v[224:225], s[0:1], 1, v[4:5]
	s_lshl_b32 s0, s12, 4
	v_bfe_u32 v2, v36, 2, 4
	v_and_or_b32 v2, s0, 48, v2
	s_ashr_i32 s0, s5, 3
	s_andn2_b32 s0, s0, 31
	v_lshlrev_b32_e32 v2, 12, v2
	s_ashr_i32 s1, s0, 31
	s_lshl_b32 s4, s12, 10
	v_lshl_add_u64 v[4:5], s[38:39], 0, v[2:3]
	v_lshlrev_b32_e32 v235, 3, v36
	s_cmp_lg_u32 0, -1
	v_lshl_add_u64 v[4:5], s[0:1], 1, v[4:5]
	v_and_b32_e32 v236, 24, v235
	s_cselect_b32 s0, 0, 0
	v_lshlrev_b32_e32 v2, 1, v236
	s_add_i32 s15, s4, s0
	s_mov_b32 s0, m0
	s_mov_b32 m0, s15
	s_nop 0
	global_load_lds_dwordx4 v[224:225], off
	s_mov_b32 m0, s0
	v_and_b32_e32 v233, 31, v36
	v_lshl_add_u64 v[226:227], v[4:5], 0, v[2:3]
	s_add_i32 s31, s15, 0x6000
	s_mov_b32 s0, m0
	s_mov_b32 m0, s31
	s_nop 0
	global_load_lds_dwordx4 v[226:227], off
	s_mov_b32 m0, s0
	v_bfe_u32 v218, v36, 5, 1
	v_lshl_add_u64 v[228:229], v[226:227], 0, s[18:19]
	s_add_i32 s0, s15, 0x8000
	s_mov_b32 s1, m0
	s_mov_b32 m0, s0
	s_nop 0
	global_load_lds_dwordx4 v[228:229], off
	s_mov_b32 m0, s1
	v_lshlrev_b32_e32 v2, 12, v233
	v_lshl_add_u64 v[4:5], v[224:225], 0, s[20:21]
	s_add_i32 s0, s15, 0x2000
	s_mov_b32 s1, m0
	s_mov_b32 m0, s0
	s_nop 0
	global_load_lds_dwordx4 v[4:5], off
	s_mov_b32 m0, s1
	v_lshl_or_b32 v2, v218, 4, v2
	global_load_dwordx4 v[174:177], v2, s[42:43] nt
	global_load_dwordx4 v[166:169], v2, s[42:43] offset:32 nt
	global_load_dwordx4 v[154:157], v2, s[42:43] offset:64 nt
	global_load_dwordx4 v[146:149], v2, s[42:43] offset:96 nt
	v_lshlrev_b32_e32 v2, 10, v218
	v_lshlrev_b32_e32 v4, 4, v233
	v_add3_u32 v242, 0, v2, v4
	v_lshl_add_u64 v[4:5], v[224:225], 0, s[22:23]
	s_add_i32 s0, s15, 0x4000
	s_mov_b32 s1, m0
	s_mov_b32 m0, s0
	s_nop 0
	global_load_lds_dwordx4 v[4:5], off
	s_mov_b32 m0, s1
	s_waitcnt vmcnt(3) lgkmcnt(0)
	s_barrier
	ds_read_b128 v[4:7], v242
	ds_read_b128 v[20:23], v242 offset:512
	ds_read_b128 v[38:41], v242 offset:2048
	s_cmp_lg_u32 s48, 0
	s_cselect_b64 s[0:1], -1, 0
	v_lshlrev_b32_e32 v234, 2, v218
	v_or_b32_e32 v241, s44, v233
	s_and_b64 vcc, exec, s[0:1]
	s_waitcnt vmcnt(3) lgkmcnt(2)
	v_mfma_f32_32x32x16_bf16 v[4:19], v[4:7], v[174:177], 0
	s_waitcnt vmcnt(2) lgkmcnt(0)
	v_mfma_f32_32x32x16_bf16 v[4:19], v[38:41], v[166:169], v[4:19]
	ds_read_b128 v[38:41], v242 offset:2560
	v_mfma_f32_32x32x16_bf16 v[20:35], v[20:23], v[174:177], 0
	s_waitcnt lgkmcnt(0)
	v_mfma_f32_32x32x16_bf16 v[20:35], v[38:41], v[166:169], v[20:35]
	ds_read_b128 v[38:41], v242 offset:4096
	s_waitcnt vmcnt(1) lgkmcnt(0)
	v_mfma_f32_32x32x16_bf16 v[4:19], v[38:41], v[154:157], v[4:19]
	ds_read_b128 v[38:41], v242 offset:4608
	s_waitcnt lgkmcnt(0)
	v_mfma_f32_32x32x16_bf16 v[20:35], v[38:41], v[154:157], v[20:35]
	ds_read_b128 v[38:41], v242 offset:6144
	s_waitcnt vmcnt(0) lgkmcnt(0)
	v_mfma_f32_32x32x16_bf16 v[4:19], v[38:41], v[146:149], v[4:19]
	ds_read_b128 v[38:41], v242 offset:6656
	s_waitcnt lgkmcnt(0)
	v_mfma_f32_32x32x16_bf16 v[20:35], v[38:41], v[146:149], v[20:35]
	s_nop 15
	s_nop 7
	s_cbranch_vccnz .LBB0_302
	v_lshlrev_b32_e32 v2, 2, v218
	v_or_b32_e32 v37, 32, v2
	v_cmp_le_i32_e32 vcc, v37, v241
	v_or_b32_e32 v37, 33, v2
	s_nop 6
	v_cndmask_b32_e32 v20, v230, v20, vcc
	v_cmp_lt_i32_e32 vcc, v2, v241
	s_nop 1
	v_cndmask_b32_e32 v5, v230, v5, vcc
	v_cmp_le_i32_e32 vcc, v2, v241
	s_nop 1
	v_cndmask_b32_e32 v4, v230, v4, vcc
	v_cmp_le_i32_e32 vcc, v37, v241
	v_or_b32_e32 v37, 2, v2
	s_nop 0
	v_cndmask_b32_e32 v21, v230, v21, vcc
	v_cmp_le_i32_e32 vcc, v37, v241
	v_or_b32_e32 v37, 34, v2
	s_nop 0
	v_cndmask_b32_e32 v6, v230, v6, vcc
	v_cmp_le_i32_e32 vcc, v37, v241
	v_or_b32_e32 v37, 3, v2
	s_nop 0
	v_cndmask_b32_e32 v22, v230, v22, vcc
	v_cmp_le_i32_e32 vcc, v37, v241
	v_or_b32_e32 v37, 35, v2
	s_nop 0
	v_cndmask_b32_e32 v7, v230, v7, vcc
	v_cmp_le_i32_e32 vcc, v37, v241
	v_or_b32_e32 v37, 8, v2
	s_nop 0
	v_cndmask_b32_e32 v23, v230, v23, vcc
	v_cmp_le_i32_e32 vcc, v37, v241
	v_or_b32_e32 v37, 40, v2
	s_nop 0
	v_cndmask_b32_e32 v8, v230, v8, vcc
	v_cmp_le_i32_e32 vcc, v37, v241
	v_or_b32_e32 v37, 9, v2
	s_nop 0
	v_cndmask_b32_e32 v24, v230, v24, vcc
	v_cmp_le_i32_e32 vcc, v37, v241
	v_or_b32_e32 v37, 41, v2
	s_nop 0
	v_cndmask_b32_e32 v9, v230, v9, vcc
	v_cmp_le_i32_e32 vcc, v37, v241
	v_or_b32_e32 v37, 10, v2
	s_nop 0
	v_cndmask_b32_e32 v25, v230, v25, vcc
	v_cmp_le_i32_e32 vcc, v37, v241
	v_or_b32_e32 v37, 42, v2
	s_nop 0
	v_cndmask_b32_e32 v10, v230, v10, vcc
	v_cmp_le_i32_e32 vcc, v37, v241
	v_or_b32_e32 v37, 11, v2
	s_nop 0
	v_cndmask_b32_e32 v26, v230, v26, vcc
	v_cmp_le_i32_e32 vcc, v37, v241
	v_or_b32_e32 v37, 43, v2
	s_nop 0
	v_cndmask_b32_e32 v11, v230, v11, vcc
	v_cmp_le_i32_e32 vcc, v37, v241
	v_or_b32_e32 v37, 16, v2
	s_nop 0
	v_cndmask_b32_e32 v27, v230, v27, vcc
	v_cmp_le_i32_e32 vcc, v37, v241
	v_or_b32_e32 v37, 48, v2
	s_nop 0
	v_cndmask_b32_e32 v12, v230, v12, vcc
	v_cmp_le_i32_e32 vcc, v37, v241
	v_or_b32_e32 v37, 17, v2
	s_nop 0
	v_cndmask_b32_e32 v28, v230, v28, vcc
	v_cmp_le_i32_e32 vcc, v37, v241
	v_or_b32_e32 v37, 49, v2
	s_nop 0
	v_cndmask_b32_e32 v13, v230, v13, vcc
	v_cmp_le_i32_e32 vcc, v37, v241
	v_or_b32_e32 v37, 18, v2
	s_nop 0
	v_cndmask_b32_e32 v29, v230, v29, vcc
	v_cmp_le_i32_e32 vcc, v37, v241
	v_or_b32_e32 v37, 50, v2
	s_nop 0
	v_cndmask_b32_e32 v14, v230, v14, vcc
	v_cmp_le_i32_e32 vcc, v37, v241
	v_or_b32_e32 v37, 19, v2
	s_nop 0
	v_cndmask_b32_e32 v30, v230, v30, vcc
	v_cmp_le_i32_e32 vcc, v37, v241
	v_or_b32_e32 v37, 51, v2
	s_nop 0
	v_cndmask_b32_e32 v15, v230, v15, vcc
	v_cmp_le_i32_e32 vcc, v37, v241
	v_or_b32_e32 v37, 24, v2
	s_nop 0
	v_cndmask_b32_e32 v31, v230, v31, vcc
	v_cmp_le_i32_e32 vcc, v37, v241
	v_or_b32_e32 v37, 56, v2
	s_nop 0
	v_cndmask_b32_e32 v16, v230, v16, vcc
	v_cmp_le_i32_e32 vcc, v37, v241
	v_or_b32_e32 v37, 25, v2
	s_nop 0
	v_cndmask_b32_e32 v32, v230, v32, vcc
	v_cmp_le_i32_e32 vcc, v37, v241
	v_or_b32_e32 v37, 57, v2
	s_nop 0
	v_cndmask_b32_e32 v17, v230, v17, vcc
	v_cmp_le_i32_e32 vcc, v37, v241
	v_or_b32_e32 v37, 26, v2
	s_nop 0
	v_cndmask_b32_e32 v33, v230, v33, vcc
	v_cmp_le_i32_e32 vcc, v37, v241
	v_or_b32_e32 v37, 58, v2
	s_nop 0
	v_cndmask_b32_e32 v18, v230, v18, vcc
	v_cmp_le_i32_e32 vcc, v37, v241
	v_or_b32_e32 v37, 27, v2
	v_or_b32_e32 v2, 59, v2
	v_cndmask_b32_e32 v34, v230, v34, vcc
	v_cmp_le_i32_e32 vcc, v37, v241
	s_nop 1
	v_cndmask_b32_e32 v19, v230, v19, vcc
	v_cmp_le_i32_e32 vcc, v2, v241
	s_nop 1
	v_cndmask_b32_e32 v35, v230, v35, vcc

.LBB0_498:
	s_lshr_b32 s13, s95, 1
	s_bitcmp0_b32 s95, 0
	s_cselect_b32 s44, s59, s58
	s_lshl_b32 s0, s13, 7
	s_add_u32 s4, s87, s0
	s_addc_u32 s10, s88, 0
	s_waitcnt vmcnt(7) lgkmcnt(1)
	v_mov_b32_e32 v36, v0
	s_add_u32 s0, s89, s0
	s_addc_u32 s1, s90, 0
	v_readfirstlane_b32 s5, v36
	s_ashr_i32 s12, s5, 6
	s_lshl_b32 s45, s44, 8
	s_lshl_b32 s42, s12, 5
	s_add_i32 s38, s42, s45
	s_ashr_i32 s39, s38, 31
	v_and_b32_e32 v232, 63, v36
	s_lshl_b64 s[30:31], s[38:39], 12
	s_add_u32 s40, s4, s30
	v_lshlrev_b32_e32 v2, 12, v232
	s_addc_u32 s41, s10, s31
	s_waitcnt vmcnt(3)
	v_lshl_add_u64 v[4:5], s[0:1], 0, v[2:3]
	s_lshl_b32 s0, s12, 3
	s_ashr_i32 s1, s0, 31
	v_lshl_add_u64 v[224:225], s[0:1], 1, v[4:5]
	s_lshl_b32 s0, s12, 4
	v_bfe_u32 v2, v36, 2, 4
	v_and_or_b32 v2, s0, 48, v2
	s_ashr_i32 s0, s5, 3
	s_andn2_b32 s0, s0, 31
	v_lshlrev_b32_e32 v2, 12, v2
	s_ashr_i32 s1, s0, 31
	s_lshl_b32 s4, s12, 10
	v_lshl_add_u64 v[4:5], s[26:27], 0, v[2:3]
	v_lshlrev_b32_e32 v233, 3, v36
	s_cmp_lg_u32 0, -1
	v_lshl_add_u64 v[4:5], s[0:1], 1, v[4:5]
	v_and_b32_e32 v235, 24, v233
	s_cselect_b32 s0, 0, 0
	v_lshlrev_b32_e32 v2, 1, v235
	s_add_i32 s15, s4, s0
	s_mov_b32 s0, m0
	s_mov_b32 m0, s15
	s_nop 0
	global_load_lds_dwordx4 v[224:225], off
	s_mov_b32 m0, s0
	v_and_b32_e32 v234, 31, v36
	v_lshl_add_u64 v[226:227], v[4:5], 0, v[2:3]
	s_add_i32 s30, s15, 0x6000
	s_mov_b32 s0, m0
	s_mov_b32 m0, s30
	s_nop 0
	global_load_lds_dwordx4 v[226:227], off
	s_mov_b32 m0, s0
	v_bfe_u32 v218, v36, 5, 1
	v_lshl_add_u64 v[228:229], v[226:227], 0, s[16:17]
	s_add_i32 s0, s15, 0x8000
	s_mov_b32 s1, m0
	s_mov_b32 m0, s0
	s_nop 0
	global_load_lds_dwordx4 v[228:229], off
	s_mov_b32 m0, s1
	v_lshlrev_b32_e32 v2, 12, v234
	v_lshl_add_u64 v[4:5], v[224:225], 0, s[18:19]
	s_add_i32 s0, s15, 0x2000
	s_mov_b32 s1, m0
	s_mov_b32 m0, s0
	s_nop 0
	global_load_lds_dwordx4 v[4:5], off
	s_mov_b32 m0, s1
	v_lshl_or_b32 v2, v218, 4, v2
	global_load_dwordx4 v[174:177], v2, s[40:41] nt
	global_load_dwordx4 v[166:169], v2, s[40:41] offset:32 nt
	global_load_dwordx4 v[158:161], v2, s[40:41] offset:64 nt
	global_load_dwordx4 v[150:153], v2, s[40:41] offset:96 nt
	v_lshlrev_b32_e32 v2, 10, v218
	v_lshlrev_b32_e32 v4, 4, v234
	v_add3_u32 v240, 0, v2, v4
	v_lshl_add_u64 v[4:5], v[224:225], 0, s[20:21]
	s_add_i32 s0, s15, 0x4000
	s_mov_b32 s1, m0
	s_mov_b32 m0, s0
	s_nop 0
	global_load_lds_dwordx4 v[4:5], off
	s_mov_b32 m0, s1
	s_waitcnt vmcnt(3) lgkmcnt(0)
	s_barrier
	ds_read_b128 v[4:7], v240
	s_waitcnt vmcnt(4)
	ds_read_b128 v[8:11], v240 offset:512
	s_waitcnt vmcnt(10)
	ds_read_b128 v[38:41], v240 offset:2048
	s_waitcnt vmcnt(9)
	ds_read_b128 v[42:45], v240 offset:2560
	s_cmp_lg_u32 s44, 0
	s_cselect_b64 s[0:1], -1, 0
	v_or_b32_e32 v239, s42, v234
	s_and_b64 vcc, exec, s[0:1]
	s_waitcnt vmcnt(3) lgkmcnt(3)
	v_mfma_f32_32x32x16_bf16 v[20:35], v[4:7], v[174:177], 0
	s_waitcnt lgkmcnt(2)
	v_mfma_f32_32x32x16_bf16 v[4:19], v[8:11], v[174:177], 0
	s_waitcnt vmcnt(2) lgkmcnt(1)
	v_mfma_f32_32x32x16_bf16 v[20:35], v[38:41], v[166:169], v[20:35]
	s_waitcnt lgkmcnt(0)
	v_mfma_f32_32x32x16_bf16 v[4:19], v[42:45], v[166:169], v[4:19]
	ds_read_b128 v[38:41], v240 offset:4096
	ds_read_b128 v[42:45], v240 offset:4608
	s_waitcnt vmcnt(1) lgkmcnt(1)
	v_mfma_f32_32x32x16_bf16 v[20:35], v[38:41], v[158:161], v[20:35]
	s_waitcnt lgkmcnt(0)
	v_mfma_f32_32x32x16_bf16 v[4:19], v[42:45], v[158:161], v[4:19]
	ds_read_b128 v[38:41], v240 offset:6144
	ds_read_b128 v[42:45], v240 offset:6656
	s_waitcnt vmcnt(0) lgkmcnt(1)
	v_mfma_f32_32x32x16_bf16 v[20:35], v[38:41], v[150:153], v[20:35]
	s_waitcnt lgkmcnt(0)
	v_mfma_f32_32x32x16_bf16 v[4:19], v[42:45], v[150:153], v[4:19]
	s_nop 15
	s_nop 7
	s_cbranch_vccnz .LBB0_500
	v_lshlrev_b32_e32 v2, 2, v218
	v_or_b32_e32 v37, 32, v2
	v_cmp_le_i32_e32 vcc, v37, v239
	v_or_b32_e32 v37, 33, v2
	s_nop 6
	v_cndmask_b32_e32 v4, v231, v4, vcc
	v_cmp_lt_i32_e32 vcc, v2, v239
	s_nop 1
	v_cndmask_b32_e32 v21, v231, v21, vcc
	v_cmp_le_i32_e32 vcc, v2, v239
	s_nop 1
	v_cndmask_b32_e32 v20, v231, v20, vcc
	v_cmp_le_i32_e32 vcc, v37, v239
	v_or_b32_e32 v37, 2, v2
	s_nop 0
	v_cndmask_b32_e32 v5, v231, v5, vcc
	v_cmp_le_i32_e32 vcc, v37, v239
	v_or_b32_e32 v37, 34, v2
	s_nop 0
	v_cndmask_b32_e32 v22, v231, v22, vcc
	v_cmp_le_i32_e32 vcc, v37, v239
	v_or_b32_e32 v37, 3, v2
	s_nop 0
	v_cndmask_b32_e32 v6, v231, v6, vcc
	v_cmp_le_i32_e32 vcc, v37, v239
	v_or_b32_e32 v37, 35, v2
	s_nop 0
	v_cndmask_b32_e32 v23, v231, v23, vcc
	v_cmp_le_i32_e32 vcc, v37, v239
	v_or_b32_e32 v37, 8, v2
	s_nop 0
	v_cndmask_b32_e32 v7, v231, v7, vcc
	v_cmp_le_i32_e32 vcc, v37, v239
	v_or_b32_e32 v37, 40, v2
	s_nop 0
	v_cndmask_b32_e32 v24, v231, v24, vcc
	v_cmp_le_i32_e32 vcc, v37, v239
	v_or_b32_e32 v37, 9, v2
	s_nop 0
	v_cndmask_b32_e32 v8, v231, v8, vcc
	v_cmp_le_i32_e32 vcc, v37, v239
	v_or_b32_e32 v37, 41, v2
	s_nop 0
	v_cndmask_b32_e32 v25, v231, v25, vcc
	v_cmp_le_i32_e32 vcc, v37, v239
	v_or_b32_e32 v37, 10, v2
	s_nop 0
	v_cndmask_b32_e32 v9, v231, v9, vcc
	v_cmp_le_i32_e32 vcc, v37, v239
	v_or_b32_e32 v37, 42, v2
	s_nop 0
	v_cndmask_b32_e32 v26, v231, v26, vcc
	v_cmp_le_i32_e32 vcc, v37, v239
	v_or_b32_e32 v37, 11, v2
	s_nop 0
	v_cndmask_b32_e32 v10, v231, v10, vcc
	v_cmp_le_i32_e32 vcc, v37, v239
	v_or_b32_e32 v37, 43, v2
	s_nop 0
	v_cndmask_b32_e32 v27, v231, v27, vcc
	v_cmp_le_i32_e32 vcc, v37, v239
	v_or_b32_e32 v37, 16, v2
	s_nop 0
	v_cndmask_b32_e32 v11, v231, v11, vcc
	v_cmp_le_i32_e32 vcc, v37, v239
	v_or_b32_e32 v37, 48, v2
	s_nop 0
	v_cndmask_b32_e32 v28, v231, v28, vcc
	v_cmp_le_i32_e32 vcc, v37, v239
	v_or_b32_e32 v37, 17, v2
	s_nop 0
	v_cndmask_b32_e32 v12, v231, v12, vcc
	v_cmp_le_i32_e32 vcc, v37, v239
	v_or_b32_e32 v37, 49, v2
	s_nop 0
	v_cndmask_b32_e32 v29, v231, v29, vcc
	v_cmp_le_i32_e32 vcc, v37, v239
	v_or_b32_e32 v37, 18, v2
	s_nop 0
	v_cndmask_b32_e32 v13, v231, v13, vcc
	v_cmp_le_i32_e32 vcc, v37, v239
	v_or_b32_e32 v37, 50, v2
	s_nop 0
	v_cndmask_b32_e32 v30, v231, v30, vcc
	v_cmp_le_i32_e32 vcc, v37, v239
	v_or_b32_e32 v37, 19, v2
	s_nop 0
	v_cndmask_b32_e32 v14, v231, v14, vcc
	v_cmp_le_i32_e32 vcc, v37, v239
	v_or_b32_e32 v37, 51, v2
	s_nop 0
	v_cndmask_b32_e32 v31, v231, v31, vcc
	v_cmp_le_i32_e32 vcc, v37, v239
	v_or_b32_e32 v37, 24, v2
	s_nop 0
	v_cndmask_b32_e32 v15, v231, v15, vcc
	v_cmp_le_i32_e32 vcc, v37, v239
	v_or_b32_e32 v37, 56, v2
	s_nop 0
	v_cndmask_b32_e32 v32, v231, v32, vcc
	v_cmp_le_i32_e32 vcc, v37, v239
	v_or_b32_e32 v37, 25, v2
	s_nop 0
	v_cndmask_b32_e32 v16, v231, v16, vcc
	v_cmp_le_i32_e32 vcc, v37, v239
	v_or_b32_e32 v37, 57, v2
	s_nop 0
	v_cndmask_b32_e32 v33, v231, v33, vcc
	v_cmp_le_i32_e32 vcc, v37, v239
	v_or_b32_e32 v37, 26, v2
	s_nop 0
	v_cndmask_b32_e32 v17, v231, v17, vcc
	v_cmp_le_i32_e32 vcc, v37, v239
	v_or_b32_e32 v37, 58, v2
	s_nop 0
	v_cndmask_b32_e32 v34, v231, v34, vcc
	v_cmp_le_i32_e32 vcc, v37, v239
	v_or_b32_e32 v37, 27, v2
	v_or_b32_e32 v2, 59, v2
	v_cndmask_b32_e32 v18, v231, v18, vcc
	v_cmp_le_i32_e32 vcc, v37, v239
	s_nop 1
	v_cndmask_b32_e32 v35, v231, v35, vcc
	v_cmp_le_i32_e32 vcc, v2, v239
	s_nop 1
	v_cndmask_b32_e32 v19, v231, v19, vcc
